# intra-XCC seams P5->P6, P7->P8, P8->P9, P9->P10 synchronise only the four workgroups sharing a 256-token row block (one monotonic counter per group) instead of the whole XCC
# speedup vs baseline: 1.0079x; 1.0079x over previous
.LBB0_697:
	s_waitcnt vmcnt(0)
	s_and_b64 vcc, exec, s[66:67]
	s_barrier
	s_cbranch_vccnz .LBB0_752
	s_cmp_lg_u32 s98, 0
	s_cbranch_scc0 .Lgp_orig_g752
	v_readlane_b32 s99, v255, 10
	s_nop 3
	s_and_b32 s99, s99, 63
	s_lshl_b32 s99, s99, 5
	s_add_i32 s99, s99, 0xfa0f300
	v_mov_b32_e32 v0, s99
	v_mov_b32_e32 v1, 1
	v_mov_b32_e32 v3, 4
	s_mov_b32 s99, 0
	s_mov_b64 s[100:101], exec
	s_mov_b64 exec, 1
	global_atomic_add v0, v1, s[74:75]
.Lgp_poll_g752:
	global_load_dword v2, v0, s[74:75] sc1
	s_waitcnt vmcnt(0)
	v_cmp_ge_u32_e32 vcc, v2, v3
	s_cbranch_vccnz .Lgp_done_g752
	s_sleep 1
	s_add_i32 s99, s99, 1
	s_cmp_lt_u32 s99, 0x100000
	s_cbranch_scc1 .Lgp_poll_g752

.Lgp_orig_g752:
	v_mbcnt_lo_u32_b32 v0, -1, 0
	v_mbcnt_hi_u32_b32 v0, -1, v0
	s_nop 0
	v_cmp_eq_u32_e32 vcc, 0, v0
	s_and_saveexec_b64 s[0:1], vcc
	s_cbranch_execz .LBB0_751
	s_add_i32 s2, 0, 0x21000
	v_mov_b32_e32 v0, s2
	s_waitcnt vmcnt(0) expcnt(0) lgkmcnt(0)
	ds_read_b32 v2, v0
	s_add_i32 s2, 0, 0x21004
	v_mov_b32_e32 v0, s2
	ds_read_b32 v0, v0
	s_waitcnt lgkmcnt(1)
	v_cmp_ne_u32_e32 vcc, 0, v2
	s_cbranch_vccnz .LBB0_715
	s_add_u32 s6, s74, 0xfa00200
	s_addc_u32 s7, s75, 0
	s_add_u32 s8, s74, 0xfa00400
	s_addc_u32 s9, s75, 0
	s_add_u32 s10, s74, 0xfa00500
	s_addc_u32 s11, s75, 0
	s_add_u32 s12, s74, 0xfa00600
	s_addc_u32 s13, s75, 0
	s_add_u32 s14, s74, 0xfa00700
	s_addc_u32 s15, s75, 0
	s_add_u32 s16, s74, 0xfa00800
	s_addc_u32 s17, s75, 0
	s_add_u32 s18, s74, 0xfa00900
	s_addc_u32 s19, s75, 0
	s_add_u32 s20, s74, 0xfa00a00
	s_addc_u32 s21, s75, 0
	s_add_u32 s22, s74, 0xfa00b00
	s_addc_u32 s23, s75, 0
	s_add_u32 s24, s74, 0xfa00c00
	s_addc_u32 s25, s75, 0
	s_add_u32 s26, s74, 0xfa00d00
	s_addc_u32 s27, s75, 0
	s_add_u32 s28, s74, 0xfa00e00
	s_addc_u32 s29, s75, 0
	s_add_u32 s30, s74, 0xfa00f00
	s_addc_u32 s31, s75, 0
	s_add_u32 s34, s74, 0xfa01000
	s_addc_u32 s35, s75, 0
	s_add_u32 s36, s74, 0xfa01100
	s_addc_u32 s37, s75, 0
	s_add_u32 s38, s74, 0xfa01200
	v_readlane_b32 s2, v254, 4
	s_addc_u32 s39, s75, 0
	s_mul_i32 s2, s79, s2
	s_add_u32 s46, s74, 0xfa01300
	s_mul_i32 s2, s2, s78
	s_addc_u32 s47, s75, 0
	s_mov_b32 s3, 1
	v_mov_b32_e32 v16, 0
	s_branch .LBB0_703

.LBB0_844:
	s_barrier
	s_waitcnt vmcnt(0)
	s_and_b64 vcc, exec, s[66:67]
	s_barrier
	s_cbranch_vccnz .LBB0_898
	s_cmp_lg_u32 s98, 0
	s_cbranch_scc0 .Lgp_orig_g898
	v_readlane_b32 s99, v255, 10
	s_nop 3
	s_and_b32 s99, s99, 63
	s_lshl_b32 s99, s99, 5
	s_add_i32 s99, s99, 0xfa0f300
	v_mov_b32_e32 v0, s99
	v_mov_b32_e32 v1, 1
	v_mov_b32_e32 v3, 8
	s_mov_b32 s99, 0
	s_mov_b64 s[100:101], exec
	s_mov_b64 exec, 1
	global_atomic_add v0, v1, s[74:75]

.Lgp_orig_g898:
	v_mbcnt_lo_u32_b32 v0, -1, 0
	v_mbcnt_hi_u32_b32 v0, -1, v0
	s_nop 0
	v_cmp_eq_u32_e32 vcc, 0, v0
	s_and_saveexec_b64 s[0:1], vcc
	s_cbranch_execz .LBB0_897
	s_add_i32 s4, 0, 0x21000
	v_mov_b32_e32 v0, s4
	s_waitcnt vmcnt(0) expcnt(0) lgkmcnt(0)
	ds_read_b32 v2, v0
	s_add_i32 s4, 0, 0x21004
	v_mov_b32_e32 v0, s4
	ds_read_b32 v0, v0
	s_waitcnt lgkmcnt(1)
	v_cmp_ne_u32_e32 vcc, 0, v2
	s_cbranch_vccnz .LBB0_861
	v_readlane_b32 s4, v254, 4
	s_mul_i32 s33, s79, s4
	s_add_u32 s4, s74, 0xfa00200
	s_addc_u32 s5, s75, 0
	s_add_u32 s6, s74, 0xfa00400
	s_addc_u32 s7, s75, 0
	s_add_u32 s8, s74, 0xfa00500
	s_addc_u32 s9, s75, 0
	s_add_u32 s10, s74, 0xfa00600
	s_addc_u32 s11, s75, 0
	s_add_u32 s12, s74, 0xfa00700
	s_addc_u32 s13, s75, 0
	s_add_u32 s14, s74, 0xfa00800
	s_addc_u32 s15, s75, 0
	s_add_u32 s16, s74, 0xfa00900
	s_addc_u32 s17, s75, 0
	s_add_u32 s18, s74, 0xfa00a00
	s_addc_u32 s19, s75, 0
	s_add_u32 s20, s74, 0xfa00b00
	s_addc_u32 s21, s75, 0
	s_add_u32 s22, s74, 0xfa00c00
	s_addc_u32 s23, s75, 0
	s_add_u32 s24, s74, 0xfa00d00
	s_addc_u32 s25, s75, 0
	s_add_u32 s26, s74, 0xfa00e00
	s_addc_u32 s27, s75, 0
	s_add_u32 s28, s74, 0xfa00f00
	s_addc_u32 s29, s75, 0
	s_add_u32 s30, s74, 0xfa01000
	s_addc_u32 s31, s75, 0
	s_add_u32 s34, s74, 0xfa01100
	s_addc_u32 s35, s75, 0
	s_add_u32 s36, s74, 0xfa01200
	s_addc_u32 s37, s75, 0
	s_add_u32 s38, s74, 0xfa01300
	s_mul_i32 s33, s33, s78
	s_addc_u32 s39, s75, 0
	s_mov_b32 s40, 1
	v_mov_b32_e32 v16, 0
	s_branch .LBB0_849

.LBB0_940:
	s_waitcnt vmcnt(0)
	s_and_b64 vcc, exec, s[66:67]
	s_barrier
	s_cbranch_vccnz .LBB0_994
	s_cmp_lg_u32 s98, 0
	s_cbranch_scc0 .Lgp_orig_g994
	v_readlane_b32 s99, v255, 10
	s_nop 3
	s_and_b32 s99, s99, 63
	s_lshl_b32 s99, s99, 5
	s_add_i32 s99, s99, 0xfa0f300
	v_mov_b32_e32 v0, s99
	v_mov_b32_e32 v1, 1
	v_mov_b32_e32 v3, 12
	s_mov_b32 s99, 0
	s_mov_b64 s[100:101], exec
	s_mov_b64 exec, 1
	global_atomic_add v0, v1, s[74:75]

.Lgp_orig_g994:
	v_mbcnt_lo_u32_b32 v0, -1, 0
	v_mbcnt_hi_u32_b32 v0, -1, v0
	s_nop 0
	v_cmp_eq_u32_e32 vcc, 0, v0
	s_and_saveexec_b64 s[0:1], vcc
	s_cbranch_execz .LBB0_993
	s_add_i32 s2, 0, 0x21000
	v_mov_b32_e32 v0, s2
	s_waitcnt vmcnt(0) expcnt(0) lgkmcnt(0)
	ds_read_b32 v2, v0
	s_add_i32 s2, 0, 0x21004
	v_mov_b32_e32 v0, s2
	ds_read_b32 v0, v0
	s_waitcnt lgkmcnt(1)
	v_cmp_ne_u32_e32 vcc, 0, v2
	s_cbranch_vccnz .LBB0_957
	s_add_u32 s4, s74, 0xfa00200
	s_addc_u32 s5, s75, 0
	s_add_u32 s6, s74, 0xfa00400
	s_addc_u32 s7, s75, 0
	s_add_u32 s10, s74, 0xfa00500
	s_addc_u32 s11, s75, 0
	s_add_u32 s12, s74, 0xfa00600
	s_addc_u32 s13, s75, 0
	s_add_u32 s14, s74, 0xfa00700
	s_addc_u32 s15, s75, 0
	s_add_u32 s16, s74, 0xfa00800
	s_addc_u32 s17, s75, 0
	s_add_u32 s18, s74, 0xfa00900
	s_addc_u32 s19, s75, 0
	s_add_u32 s20, s74, 0xfa00a00
	s_addc_u32 s21, s75, 0
	s_add_u32 s22, s74, 0xfa00b00
	s_addc_u32 s23, s75, 0
	s_add_u32 s24, s74, 0xfa00c00
	s_addc_u32 s25, s75, 0
	s_add_u32 s26, s74, 0xfa00d00
	s_addc_u32 s27, s75, 0
	s_add_u32 s28, s74, 0xfa00e00
	s_addc_u32 s29, s75, 0
	s_add_u32 s30, s74, 0xfa00f00
	s_addc_u32 s31, s75, 0
	s_add_u32 s34, s74, 0xfa01000
	s_addc_u32 s35, s75, 0
	s_add_u32 s36, s74, 0xfa01100
	s_addc_u32 s37, s75, 0
	s_add_u32 s38, s74, 0xfa01200
	v_readlane_b32 s2, v254, 4
	s_addc_u32 s39, s75, 0
	s_mul_i32 s2, s79, s2
	s_add_u32 s44, s74, 0xfa01300
	s_mul_i32 s2, s2, s78
	s_addc_u32 s45, s75, 0
	s_mov_b32 s3, 1
	v_mov_b32_e32 v16, 0
	s_branch .LBB0_945

.LBB0_1010:
	s_waitcnt vmcnt(0)
	s_and_b64 vcc, exec, s[66:67]
	s_barrier
	s_cbranch_vccnz .LBB0_1064
	s_cmp_lg_u32 s98, 0
	s_cbranch_scc0 .Lgp_orig_g1064
	v_readlane_b32 s99, v255, 10
	s_nop 3
	s_and_b32 s99, s99, 63
	s_lshl_b32 s99, s99, 5
	s_add_i32 s99, s99, 0xfa0f300
	v_mov_b32_e32 v0, s99
	v_mov_b32_e32 v1, 1
	v_mov_b32_e32 v3, 16
	s_mov_b32 s99, 0
	s_mov_b64 s[100:101], exec
	s_mov_b64 exec, 1
	global_atomic_add v0, v1, s[74:75]

.Lgp_orig_g1064:
	v_mbcnt_lo_u32_b32 v0, -1, 0
	v_mbcnt_hi_u32_b32 v0, -1, v0
	s_nop 0
	v_cmp_eq_u32_e32 vcc, 0, v0
	s_and_saveexec_b64 s[0:1], vcc
	s_cbranch_execz .LBB0_1063
	s_add_i32 s2, 0, 0x21000
	v_mov_b32_e32 v0, s2
	s_waitcnt vmcnt(0) expcnt(0) lgkmcnt(0)
	ds_read_b32 v2, v0
	s_add_i32 s2, 0, 0x21004
	v_mov_b32_e32 v0, s2
	ds_read_b32 v0, v0
	s_waitcnt lgkmcnt(1)
	v_cmp_ne_u32_e32 vcc, 0, v2
	s_cbranch_vccnz .LBB0_1027
	s_add_u32 s4, s74, 0xfa00200
	s_addc_u32 s5, s75, 0
	s_add_u32 s6, s74, 0xfa00400
	s_addc_u32 s7, s75, 0
	s_add_u32 s8, s74, 0xfa00500
	s_addc_u32 s9, s75, 0
	s_add_u32 s10, s74, 0xfa00600
	s_addc_u32 s11, s75, 0
	s_add_u32 s12, s74, 0xfa00700
	s_addc_u32 s13, s75, 0
	s_add_u32 s14, s74, 0xfa00800
	s_addc_u32 s15, s75, 0
	s_add_u32 s16, s74, 0xfa00900
	s_addc_u32 s17, s75, 0
	s_add_u32 s18, s74, 0xfa00a00
	s_addc_u32 s19, s75, 0
	s_add_u32 s20, s74, 0xfa00b00
	s_addc_u32 s21, s75, 0
	s_add_u32 s22, s74, 0xfa00c00
	s_addc_u32 s23, s75, 0
	s_add_u32 s24, s74, 0xfa00d00
	s_addc_u32 s25, s75, 0
	s_add_u32 s26, s74, 0xfa00e00
	s_addc_u32 s27, s75, 0
	s_add_u32 s28, s74, 0xfa00f00
	s_addc_u32 s29, s75, 0
	s_add_u32 s30, s74, 0xfa01000
	s_addc_u32 s31, s75, 0
	s_add_u32 s34, s74, 0xfa01100
	s_addc_u32 s35, s75, 0
	s_add_u32 s36, s74, 0xfa01200
	v_readlane_b32 s2, v254, 4
	s_addc_u32 s37, s75, 0
	s_mul_i32 s2, s79, s2
	s_add_u32 s38, s74, 0xfa01300
	s_mul_i32 s2, s2, s78
	s_addc_u32 s39, s75, 0
	s_mov_b32 s3, 1
	v_mov_b32_e32 v16, 0
	s_branch .LBB0_1015
.LBB0_1014:
	s_and_b64 vcc, exec, s[44:45]
	s_cbranch_vccnz .LBB0_1022
